# dil_combine: log-sum-exp and gate-row loads issued together
# speedup vs baseline: 1.0104x; 1.0020x over previous
.LBB0_1332:
	v_bfe_u32 v12, v5, 3, 2
	v_ashrrev_i32_e32 v2, 5, v5
	v_lshlrev_b32_e32 v0, 16, v12
	v_ashrrev_i32_e32 v3, 31, v2
	v_lshl_add_u64 v[6:7], s[8:9], 0, v[0:1]
	v_lshl_add_u64 v[6:7], v[2:3], 2, v[6:7]
	v_add_co_u32_e32 v10, vcc, 0x40000, v6
	global_load_dword v0, v[6:7], off
	s_nop 0
	v_addc_co_u32_e32 v11, vcc, 0, v7, vcc
	global_load_dword v4, v[10:11], off
	v_add_co_u32_e32 v6, vcc, s50, v6
	v_mov_b32_e32 v23, v1
	s_nop 0
	v_addc_co_u32_e32 v7, vcc, 0, v7, vcc
	global_load_dword v8, v[6:7], off
	v_mov_b64_e32 v[68:69], s[6:7]
	v_mad_i64_i32 v[68:69], s[14:15], v2, s63, v[68:69]
	v_lshlrev_b32_e32 v70, 7, v12
	v_mov_b32_e32 v71, 0
	v_lshl_add_u64 v[68:69], v[68:69], 0, v[70:71]
	v_and_b32_e32 v70, 56, v9
	v_lshlrev_b32_e32 v70, 1, v70
	v_lshl_add_u64 v[68:69], v[68:69], 0, v[70:71]
	global_load_dwordx4 v[72:75], v[68:69], off
	global_load_dwordx4 v[76:79], v[68:69], off offset:512
	global_load_dwordx4 v[80:83], v[68:69], off offset:1024
	s_waitcnt vmcnt(3)
	v_max3_f32 v10, v0, v4, v8
	v_sub_f32_e32 v0, v0, v10
	v_exp_f32_e32 v7, v0
	v_sub_f32_e32 v0, v4, v10
	v_exp_f32_e32 v6, v0
	v_sub_f32_e32 v0, v8, v10
	v_exp_f32_e32 v0, v0
	v_add_f32_e32 v4, v7, v6
	v_add_f32_e32 v4, v0, v4
	v_div_scale_f32 v8, s[14:15], v4, v4, 1.0
	v_rcp_f32_e32 v10, v8
	s_nop 0
	v_fma_f32 v11, -v8, v10, 1.0
	v_fmac_f32_e32 v10, v11, v10
	v_div_scale_f32 v11, vcc, 1.0, v4, 1.0
	v_mul_f32_e32 v13, v11, v10
	v_fma_f32 v14, -v8, v13, v11
	v_fmac_f32_e32 v13, v14, v10
	v_fma_f32 v8, -v8, v13, v11
	v_div_fmas_f32 v8, v8, v10, v13
	v_div_fixup_f32 v8, v8, v4, 1.0
	v_mov_b64_e32 v[10:11], s[6:7]
	v_mul_f32_e32 v4, v0, v8
	v_mad_i64_i32 v[10:11], s[14:15], v2, s63, v[10:11]
	v_lshlrev_b32_e32 v0, 7, v12
	v_and_b32_e32 v12, 56, v9
	v_lshl_add_u64 v[10:11], v[10:11], 0, v[0:1]
	v_lshlrev_b32_e32 v22, 1, v12
	v_lshl_add_u64 v[18:19], v[10:11], 0, v[22:23]
	s_waitcnt vmcnt(0)
	v_mov_b64_e32 v[10:11], v[72:73]
	v_mov_b64_e32 v[12:13], v[74:75]
	v_mov_b64_e32 v[14:15], v[76:77]
	v_mov_b64_e32 v[16:17], v[78:79]
	s_nop 0
	v_mov_b64_e32 v[18:19], v[80:81]
	v_mov_b64_e32 v[20:21], v[82:83]
	v_pk_mul_f32 v[6:7], v[6:7], v[8:9] op_sel_hi:[1,0]
	v_lshlrev_b64 v[2:3], 9, v[2:3]
	v_lshl_add_u64 v[2:3], s[10:11], 0, v[2:3]
	s_mov_b32 s14, 0x7ffff
	v_lshl_add_u64 v[2:3], v[2:3], 0, v[0:1]
	v_lshl_add_u64 v[2:3], v[2:3], 0, v[22:23]
	v_add_u32_e32 v9, s58, v9
	s_waitcnt vmcnt(2)
	v_lshlrev_b32_e32 v26, 16, v10
	s_waitcnt vmcnt(1)
	v_and_b32_e32 v27, 0xffff0000, v14
	v_lshlrev_b32_e32 v24, 16, v14
	v_and_b32_e32 v25, 0xffff0000, v10
	v_pk_mul_f32 v[26:27], v[6:7], v[26:27] op_sel:[1,0] op_sel_hi:[0,1]
	s_waitcnt vmcnt(0)
	v_lshlrev_b32_e32 v28, 16, v18
	v_and_b32_e32 v29, 0xffff0000, v18
	v_pk_fma_f32 v[24:25], v[6:7], v[24:25], v[26:27]
	v_lshlrev_b32_e32 v14, 16, v11
	v_pk_fma_f32 v[24:25], v[4:5], v[28:29], v[24:25] op_sel_hi:[0,1,1]
	v_cvt_pk_bf16_f32 v10, v24, v25
	v_lshlrev_b32_e32 v24, 16, v15
	v_and_b32_e32 v15, 0xffff0000, v15
	v_and_b32_e32 v25, 0xffff0000, v11
	v_pk_mul_f32 v[14:15], v[6:7], v[14:15] op_sel:[1,0] op_sel_hi:[0,1]
	v_lshlrev_b32_e32 v18, 16, v19
	v_and_b32_e32 v19, 0xffff0000, v19
	v_pk_fma_f32 v[14:15], v[6:7], v[24:25], v[14:15]
	v_lshlrev_b32_e32 v24, 16, v20
	v_pk_fma_f32 v[14:15], v[4:5], v[18:19], v[14:15] op_sel_hi:[0,1,1]
	v_lshlrev_b32_e32 v18, 16, v12
	v_and_b32_e32 v19, 0xffff0000, v16
	v_cvt_pk_bf16_f32 v11, v14, v15
	v_lshlrev_b32_e32 v14, 16, v16
	v_and_b32_e32 v15, 0xffff0000, v12
	v_pk_mul_f32 v[18:19], v[6:7], v[18:19] op_sel:[1,0] op_sel_hi:[0,1]
	v_and_b32_e32 v25, 0xffff0000, v20
	v_pk_fma_f32 v[14:15], v[6:7], v[14:15], v[18:19]
	v_lshlrev_b32_e32 v16, 16, v13
	v_pk_fma_f32 v[14:15], v[4:5], v[24:25], v[14:15] op_sel_hi:[0,1,1]
	v_cvt_pk_bf16_f32 v12, v14, v15
	v_lshlrev_b32_e32 v14, 16, v17
	v_and_b32_e32 v17, 0xffff0000, v17
	v_and_b32_e32 v15, 0xffff0000, v13
	v_pk_mul_f32 v[16:17], v[6:7], v[16:17] op_sel:[1,0] op_sel_hi:[0,1]
	v_pk_fma_f32 v[6:7], v[6:7], v[14:15], v[16:17]
	v_lshlrev_b32_e32 v14, 16, v21
	v_and_b32_e32 v15, 0xffff0000, v21
	v_pk_fma_f32 v[6:7], v[4:5], v[14:15], v[6:7] op_sel_hi:[0,1,1]
	v_add_u32_e32 v5, s57, v5
	v_cmp_lt_i32_e32 vcc, s14, v5
	v_cvt_pk_bf16_f32 v13, v6, v7
	s_or_b64 s[12:13], vcc, s[12:13]
	global_store_dwordx4 v[2:3], v[10:13], off
	s_andn2_b64 exec, exec, s[12:13]
	s_cbranch_execnz .LBB0_1332
